# grid barrier waiters poll less often (s_sleep 6 between polls)
# speedup vs baseline: 1.0037x; 1.0037x over previous
.Lmb_spin_top:
	global_load_dword v252, v250, s[100:101] sc1
	s_waitcnt vmcnt(0)
	v_cmp_lt_u32_e32 vcc, v252, v253
	s_cbranch_vccz .Lmb_top_ok
	s_sleep 6
	v_add_u32_e32 v255, 1, v255
	v_cmp_gt_u32_e32 vcc, 0x40000, v255
	s_cbranch_vccnz .Lmb_spin_top

.Lmb_spin_loc:
	global_load_dword v252, v254, s[100:101] sc1
	s_waitcnt vmcnt(0)
	v_cmp_lt_u32_e32 vcc, v252, v253
	s_cbranch_vccz .Lmb_loc_ok
	s_sleep 6
	v_add_u32_e32 v255, 1, v255
	v_cmp_gt_u32_e32 vcc, 0x40000, v255
	s_cbranch_vccnz .Lmb_spin_loc
